# stagger: waves 4-7 sleep 8 at top of each diff-attention stage (de-lockstep SIMD partners)
# baseline (speedup 1.0000x reference)
.LBB0_303:
	v_readfirstlane_b32 s98, v164
	s_nop 0
	s_cmp_lt_u32 s98, 0x100
	s_cbranch_scc1 .Lstag_skip_0
	s_sleep 8

	.amdhsa_kernel _Z10fwd_kernel4Args
		.amdhsa_group_segment_fixed_size 0
		.amdhsa_private_segment_fixed_size 0
		.amdhsa_kernarg_size 400
		.amdhsa_user_sgpr_count 2
		.amdhsa_user_sgpr_dispatch_ptr 0
		.amdhsa_user_sgpr_queue_ptr 0
		.amdhsa_user_sgpr_kernarg_segment_ptr 1
		.amdhsa_user_sgpr_dispatch_id 0
		.amdhsa_user_sgpr_kernarg_preload_length 0
		.amdhsa_user_sgpr_kernarg_preload_offset 0
		.amdhsa_user_sgpr_private_segment_size 0
		.amdhsa_uses_dynamic_stack 0
		.amdhsa_enable_private_segment 0
		.amdhsa_system_sgpr_workgroup_id_x 1
		.amdhsa_system_sgpr_workgroup_id_y 0
		.amdhsa_system_sgpr_workgroup_id_z 0
		.amdhsa_system_sgpr_workgroup_info 0
		.amdhsa_system_vgpr_workitem_id 2
		.amdhsa_next_free_vgpr 256
		.amdhsa_next_free_sgpr 100
		.amdhsa_accum_offset 256
		.amdhsa_reserve_vcc 1
		.amdhsa_float_round_mode_32 0
		.amdhsa_float_round_mode_16_64 0
		.amdhsa_float_denorm_mode_32 3
		.amdhsa_float_denorm_mode_16_64 3
		.amdhsa_dx10_clamp 1
		.amdhsa_ieee_mode 1
		.amdhsa_fp16_overflow 0
		.amdhsa_tg_split 0
		.amdhsa_exception_fp_ieee_invalid_op 0
		.amdhsa_exception_fp_denorm_src 0
		.amdhsa_exception_fp_ieee_div_zero 0
		.amdhsa_exception_fp_ieee_overflow 0
		.amdhsa_exception_fp_ieee_underflow 0
		.amdhsa_exception_fp_ieee_inexact 0
		.amdhsa_exception_int_div_zero 0
	.end_amdhsa_kernel

amdhsa.kernels:
  - .agpr_count:     0
    .args:
      - .offset:         0
        .size:           144
        .value_kind:     by_value
      - .offset:         144
        .size:           4
        .value_kind:     hidden_block_count_x
      - .offset:         148
        .size:           4
        .value_kind:     hidden_block_count_y
      - .offset:         152
        .size:           4
        .value_kind:     hidden_block_count_z
      - .offset:         156
        .size:           2
        .value_kind:     hidden_group_size_x
      - .offset:         158
        .size:           2
        .value_kind:     hidden_group_size_y
      - .offset:         160
        .size:           2
        .value_kind:     hidden_group_size_z
      - .offset:         162
        .size:           2
        .value_kind:     hidden_remainder_x
      - .offset:         164
        .size:           2
        .value_kind:     hidden_remainder_y
      - .offset:         166
        .size:           2
        .value_kind:     hidden_remainder_z
      - .offset:         184
        .size:           8
        .value_kind:     hidden_global_offset_x
      - .offset:         192
        .size:           8
        .value_kind:     hidden_global_offset_y
      - .offset:         200
        .size:           8
        .value_kind:     hidden_global_offset_z
      - .offset:         208
        .size:           2
        .value_kind:     hidden_grid_dims
      - .offset:         232
        .size:           8
        .value_kind:     hidden_multigrid_sync_arg
      - .offset:         264
        .size:           4
        .value_kind:     hidden_dynamic_lds_size
    .group_segment_fixed_size: 0
    .kernarg_segment_align: 8
    .kernarg_segment_size: 400
    .language:       OpenCL C
    .language_version:
      - 2
      - 0
    .max_flat_workgroup_size: 512
    .name:           _Z10fwd_kernel4Args
    .private_segment_fixed_size: 0
    .sgpr_count:     106
    .sgpr_spill_count: 219
    .symbol:         _Z10fwd_kernel4Args.kd
    .uniform_work_group_size: 1
    .uses_dynamic_stack: false
    .vgpr_count:     256
    .vgpr_spill_count: 0
    .wavefront_size: 64
